# v57 + main W_o units' bf16 y stores written through (sc0 sc1): write-back overlaps the unit instead of the mixer-end barrier flush
# baseline (speedup 1.0000x reference)
; __device__ __forceinline__ unsigned cvt_pk_bf16(float lo, float hi) { unsigned r; asm volatile("v_cvt_pk_bf16_f32 %0, %1, %2" : "=v"(r) : "v"(lo), "v"(hi)); return r; }
;     __device__ __forceinline__ void operator()(const f32x4 (&acc)[2][2][4][2], const Unit& u, int wr, int wc, int fr, int fq) const {
;     ...
;             for (int m = 0; m < 4; ++m) { const int row = row0 + ai * HALF + m * 16; bf16_t* rowp = O + (size_t)row * DM + col0;
;                 float sc = 1.0f; if (SEG) { if (ftab) sc = ftab[(ai * HALF + wr * 64 + m * 16 + fr) * 4 + 2];
;                     else { const float s2 = ss[(size_t)row * 4 + 2]; sc = 1.0f / sqrtf(s2 * (1.0f / 384.0f) + LN_EPS); } }
; #pragma unroll
;                 for (int bj = 0; bj < 2; ++bj) { const f32x4 v0 = acc[ai][bj][m][0] * sc, v1 = acc[ai][bj][m][1] * sc;
;                     u32x4 wv; wv.x = cvt_pk_bf16(v0[0], v0[1]); wv.y = cvt_pk_bf16(v0[2], v0[3]); wv.z = cvt_pk_bf16(v1[0], v1[1]); wv.w = cvt_pk_bf16(v1[2], v1[3]);
;                     *(u32x4*)(rowp + bj * HALF) = wv; } }
.LBB0_498:
	s_add_u32 s6, s10, 0xc300000
	s_addc_u32 s7, s11, 0
	v_lshlrev_b64 v[140:141], 11, v[144:145]
	v_lshl_add_u64 v[140:141], s[6:7], 0, v[140:141]
	v_lshlrev_b32_e32 v0, 1, v150
	v_lshl_add_u64 v[140:141], v[140:141], 0, v[0:1]
	s_waitcnt lgkmcnt(0)
	v_pk_mul_f32 v[132:133], v[132:133], v[138:139] op_sel_hi:[1,0]
	v_pk_mul_f32 v[130:131], v[130:131], v[138:139] op_sel_hi:[1,0]
	v_pk_mul_f32 v[142:143], v[128:129], v[138:139] op_sel_hi:[1,0]
	v_pk_mul_f32 v[128:129], v[126:127], v[138:139] op_sel_hi:[1,0]
	v_cvt_pk_bf16_f32 v126, v130, v131
	v_cvt_pk_bf16_f32 v127, v132, v133
	v_pk_mul_f32 v[122:123], v[122:123], v[138:139] op_sel_hi:[1,0]
	v_cvt_pk_bf16_f32 v128, v128, v129
	v_cvt_pk_bf16_f32 v129, v142, v143
	flat_store_dwordx4 v[140:141], v[126:129] sc0 sc1
	s_and_b64 vcc, exec, s[4:5]
	s_mov_b64 s[0:1], -1
	v_pk_mul_f32 v[126:127], v[120:121], v[138:139] op_sel_hi:[1,0]
	v_pk_mul_f32 v[120:121], v[118:119], v[138:139] op_sel_hi:[1,0]
	v_cvt_pk_bf16_f32 v118, v122, v123
	v_pk_mul_f32 v[124:125], v[124:125], v[138:139] op_sel_hi:[1,0]
	s_nop 0
	v_cvt_pk_bf16_f32 v119, v124, v125
	v_cvt_pk_bf16_f32 v120, v120, v121
	v_cvt_pk_bf16_f32 v121, v126, v127
	flat_store_dwordx4 v[140:141], v[118:121] offset:256 sc0 sc1
	s_cbranch_vccnz .LBB0_500
	ds_read_b32 v118, v17 offset:264
	s_mov_b64 s[0:1], 0

; __device__ __forceinline__ unsigned cvt_pk_bf16(float lo, float hi) { unsigned r; asm volatile("v_cvt_pk_bf16_f32 %0, %1, %2" : "=v"(r) : "v"(lo), "v"(hi)); return r; }
;     __device__ __forceinline__ void operator()(const f32x4 (&acc)[2][2][4][2], const Unit& u, int wr, int wc, int fr, int fq) const {
;     ...
;             for (int m = 0; m < 4; ++m) { const int row = row0 + ai * HALF + m * 16; bf16_t* rowp = O + (size_t)row * DM + col0;
;                 float sc = 1.0f; if (SEG) { if (ftab) sc = ftab[(ai * HALF + wr * 64 + m * 16 + fr) * 4 + 2];
;                     else { const float s2 = ss[(size_t)row * 4 + 2]; sc = 1.0f / sqrtf(s2 * (1.0f / 384.0f) + LN_EPS); } }
; #pragma unroll
;                 for (int bj = 0; bj < 2; ++bj) { const f32x4 v0 = acc[ai][bj][m][0] * sc, v1 = acc[ai][bj][m][1] * sc;
;                     u32x4 wv; wv.x = cvt_pk_bf16(v0[0], v0[1]); wv.y = cvt_pk_bf16(v0[2], v0[3]); wv.z = cvt_pk_bf16(v1[0], v1[1]); wv.w = cvt_pk_bf16(v1[2], v1[3]);
;                     *(u32x4*)(rowp + bj * HALF) = wv; } }
.LBB0_502:
	v_lshlrev_b64 v[120:121], 11, v[136:137]
	v_lshl_add_u64 v[120:121], s[6:7], 0, v[120:121]
	v_lshl_add_u64 v[120:121], v[120:121], 0, v[0:1]
	s_waitcnt lgkmcnt(0)
	v_pk_mul_f32 v[116:117], v[116:117], v[118:119] op_sel_hi:[1,0]
	v_pk_mul_f32 v[114:115], v[114:115], v[118:119] op_sel_hi:[1,0]
	v_pk_mul_f32 v[122:123], v[112:113], v[118:119] op_sel_hi:[1,0]
	v_pk_mul_f32 v[112:113], v[110:111], v[118:119] op_sel_hi:[1,0]
	v_cvt_pk_bf16_f32 v110, v114, v115
	v_cvt_pk_bf16_f32 v111, v116, v117
	v_pk_mul_f32 v[106:107], v[106:107], v[118:119] op_sel_hi:[1,0]
	v_cvt_pk_bf16_f32 v112, v112, v113
	v_cvt_pk_bf16_f32 v113, v122, v123
	flat_store_dwordx4 v[120:121], v[110:113] sc0 sc1
	s_and_b64 vcc, exec, s[4:5]
	s_mov_b64 s[0:1], -1
	v_pk_mul_f32 v[110:111], v[104:105], v[118:119] op_sel_hi:[1,0]
	v_pk_mul_f32 v[104:105], v[102:103], v[118:119] op_sel_hi:[1,0]
	v_cvt_pk_bf16_f32 v102, v106, v107
	v_pk_mul_f32 v[108:109], v[108:109], v[118:119] op_sel_hi:[1,0]
	s_nop 0
	v_cvt_pk_bf16_f32 v103, v108, v109
	v_cvt_pk_bf16_f32 v104, v104, v105
	v_cvt_pk_bf16_f32 v105, v110, v111
	flat_store_dwordx4 v[120:121], v[102:105] offset:256 sc0 sc1
	s_cbranch_vccnz .LBB0_504
	ds_read_b32 v102, v17 offset:520
	s_mov_b64 s[0:1], 0

; __device__ __forceinline__ unsigned cvt_pk_bf16(float lo, float hi) { unsigned r; asm volatile("v_cvt_pk_bf16_f32 %0, %1, %2" : "=v"(r) : "v"(lo), "v"(hi)); return r; }
;     __device__ __forceinline__ void operator()(const f32x4 (&acc)[2][2][4][2], const Unit& u, int wr, int wc, int fr, int fq) const {
;     ...
;             for (int m = 0; m < 4; ++m) { const int row = row0 + ai * HALF + m * 16; bf16_t* rowp = O + (size_t)row * DM + col0;
;                 float sc = 1.0f; if (SEG) { if (ftab) sc = ftab[(ai * HALF + wr * 64 + m * 16 + fr) * 4 + 2];
;                     else { const float s2 = ss[(size_t)row * 4 + 2]; sc = 1.0f / sqrtf(s2 * (1.0f / 384.0f) + LN_EPS); } }
; #pragma unroll
;                 for (int bj = 0; bj < 2; ++bj) { const f32x4 v0 = acc[ai][bj][m][0] * sc, v1 = acc[ai][bj][m][1] * sc;
;                     u32x4 wv; wv.x = cvt_pk_bf16(v0[0], v0[1]); wv.y = cvt_pk_bf16(v0[2], v0[3]); wv.z = cvt_pk_bf16(v1[0], v1[1]); wv.w = cvt_pk_bf16(v1[2], v1[3]);
;                     *(u32x4*)(rowp + bj * HALF) = wv; } }
.LBB0_506:
	v_lshlrev_b64 v[104:105], 11, v[134:135]
	v_lshl_add_u64 v[104:105], s[6:7], 0, v[104:105]
	v_lshl_add_u64 v[104:105], v[104:105], 0, v[0:1]
	s_waitcnt lgkmcnt(0)
	v_pk_mul_f32 v[100:101], v[100:101], v[102:103] op_sel_hi:[1,0]
	v_pk_mul_f32 v[98:99], v[98:99], v[102:103] op_sel_hi:[1,0]
	v_pk_mul_f32 v[106:107], v[96:97], v[102:103] op_sel_hi:[1,0]
	v_pk_mul_f32 v[96:97], v[94:95], v[102:103] op_sel_hi:[1,0]
	v_cvt_pk_bf16_f32 v94, v98, v99
	v_cvt_pk_bf16_f32 v95, v100, v101
	v_pk_mul_f32 v[90:91], v[90:91], v[102:103] op_sel_hi:[1,0]
	v_cvt_pk_bf16_f32 v96, v96, v97
	v_cvt_pk_bf16_f32 v97, v106, v107
	flat_store_dwordx4 v[104:105], v[94:97] sc0 sc1
	s_and_b64 vcc, exec, s[4:5]
	s_mov_b64 s[0:1], -1
	v_pk_mul_f32 v[94:95], v[88:89], v[102:103] op_sel_hi:[1,0]
	v_pk_mul_f32 v[88:89], v[86:87], v[102:103] op_sel_hi:[1,0]
	v_cvt_pk_bf16_f32 v86, v90, v91
	v_pk_mul_f32 v[92:93], v[92:93], v[102:103] op_sel_hi:[1,0]
	s_nop 0
	v_cvt_pk_bf16_f32 v87, v92, v93
	v_cvt_pk_bf16_f32 v88, v88, v89
	v_cvt_pk_bf16_f32 v89, v94, v95
	flat_store_dwordx4 v[104:105], v[86:89] offset:256 sc0 sc1
	s_cbranch_vccnz .LBB0_508
	ds_read_b32 v86, v17 offset:776
	s_mov_b64 s[0:1], 0

; __device__ __forceinline__ unsigned cvt_pk_bf16(float lo, float hi) { unsigned r; asm volatile("v_cvt_pk_bf16_f32 %0, %1, %2" : "=v"(r) : "v"(lo), "v"(hi)); return r; }
;     __device__ __forceinline__ void operator()(const f32x4 (&acc)[2][2][4][2], const Unit& u, int wr, int wc, int fr, int fq) const {
;     ...
;             for (int m = 0; m < 4; ++m) { const int row = row0 + ai * HALF + m * 16; bf16_t* rowp = O + (size_t)row * DM + col0;
;                 float sc = 1.0f; if (SEG) { if (ftab) sc = ftab[(ai * HALF + wr * 64 + m * 16 + fr) * 4 + 2];
;                     else { const float s2 = ss[(size_t)row * 4 + 2]; sc = 1.0f / sqrtf(s2 * (1.0f / 384.0f) + LN_EPS); } }
; #pragma unroll
;                 for (int bj = 0; bj < 2; ++bj) { const f32x4 v0 = acc[ai][bj][m][0] * sc, v1 = acc[ai][bj][m][1] * sc;
;                     u32x4 wv; wv.x = cvt_pk_bf16(v0[0], v0[1]); wv.y = cvt_pk_bf16(v0[2], v0[3]); wv.z = cvt_pk_bf16(v1[0], v1[1]); wv.w = cvt_pk_bf16(v1[2], v1[3]);
;                     *(u32x4*)(rowp + bj * HALF) = wv; } }
.LBB0_510:
	v_lshlrev_b64 v[2:3], 11, v[2:3]
	v_lshl_add_u64 v[2:3], s[6:7], 0, v[2:3]
	v_lshl_add_u64 v[2:3], v[2:3], 0, v[0:1]
	s_waitcnt lgkmcnt(0)
	v_pk_mul_f32 v[84:85], v[84:85], v[86:87] op_sel_hi:[1,0]
	v_pk_mul_f32 v[82:83], v[82:83], v[86:87] op_sel_hi:[1,0]
	v_pk_mul_f32 v[88:89], v[80:81], v[86:87] op_sel_hi:[1,0]
	v_pk_mul_f32 v[80:81], v[78:79], v[86:87] op_sel_hi:[1,0]
	v_cvt_pk_bf16_f32 v78, v82, v83
	v_cvt_pk_bf16_f32 v79, v84, v85
	v_pk_mul_f32 v[74:75], v[74:75], v[86:87] op_sel_hi:[1,0]
	v_cvt_pk_bf16_f32 v80, v80, v81
	v_cvt_pk_bf16_f32 v81, v88, v89
	flat_store_dwordx4 v[2:3], v[78:81] sc0 sc1
	s_and_b64 vcc, exec, s[4:5]
	s_mov_b64 s[0:1], -1
	v_pk_mul_f32 v[78:79], v[72:73], v[86:87] op_sel_hi:[1,0]
	v_pk_mul_f32 v[72:73], v[70:71], v[86:87] op_sel_hi:[1,0]
	v_cvt_pk_bf16_f32 v70, v74, v75
	v_pk_mul_f32 v[76:77], v[76:77], v[86:87] op_sel_hi:[1,0]
	s_nop 0
	v_cvt_pk_bf16_f32 v71, v76, v77
	v_cvt_pk_bf16_f32 v72, v72, v73
	v_cvt_pk_bf16_f32 v73, v78, v79
	flat_store_dwordx4 v[2:3], v[70:73] offset:256 sc0 sc1
	s_cbranch_vccnz .LBB0_512
	ds_read_b32 v70, v17 offset:2056
	s_mov_b64 s[0:1], 0

; __device__ __forceinline__ unsigned cvt_pk_bf16(float lo, float hi) { unsigned r; asm volatile("v_cvt_pk_bf16_f32 %0, %1, %2" : "=v"(r) : "v"(lo), "v"(hi)); return r; }
;     __device__ __forceinline__ void operator()(const f32x4 (&acc)[2][2][4][2], const Unit& u, int wr, int wc, int fr, int fq) const {
;     ...
;             for (int m = 0; m < 4; ++m) { const int row = row0 + ai * HALF + m * 16; bf16_t* rowp = O + (size_t)row * DM + col0;
;                 float sc = 1.0f; if (SEG) { if (ftab) sc = ftab[(ai * HALF + wr * 64 + m * 16 + fr) * 4 + 2];
;                     else { const float s2 = ss[(size_t)row * 4 + 2]; sc = 1.0f / sqrtf(s2 * (1.0f / 384.0f) + LN_EPS); } }
; #pragma unroll
;                 for (int bj = 0; bj < 2; ++bj) { const f32x4 v0 = acc[ai][bj][m][0] * sc, v1 = acc[ai][bj][m][1] * sc;
;                     u32x4 wv; wv.x = cvt_pk_bf16(v0[0], v0[1]); wv.y = cvt_pk_bf16(v0[2], v0[3]); wv.z = cvt_pk_bf16(v1[0], v1[1]); wv.w = cvt_pk_bf16(v1[2], v1[3]);
;                     *(u32x4*)(rowp + bj * HALF) = wv; } }
.LBB0_514:
	v_lshlrev_b64 v[2:3], 11, v[2:3]
	v_lshl_add_u64 v[2:3], s[6:7], 0, v[2:3]
	v_lshl_add_u64 v[2:3], v[2:3], 0, v[0:1]
	s_waitcnt lgkmcnt(0)
	v_pk_mul_f32 v[68:69], v[68:69], v[70:71] op_sel_hi:[1,0]
	v_pk_mul_f32 v[66:67], v[66:67], v[70:71] op_sel_hi:[1,0]
	v_pk_mul_f32 v[72:73], v[64:65], v[70:71] op_sel_hi:[1,0]
	v_pk_mul_f32 v[64:65], v[62:63], v[70:71] op_sel_hi:[1,0]
	v_cvt_pk_bf16_f32 v62, v66, v67
	v_cvt_pk_bf16_f32 v63, v68, v69
	v_pk_mul_f32 v[58:59], v[58:59], v[70:71] op_sel_hi:[1,0]
	v_cvt_pk_bf16_f32 v64, v64, v65
	v_cvt_pk_bf16_f32 v65, v72, v73
	flat_store_dwordx4 v[2:3], v[62:65] sc0 sc1
	s_and_b64 vcc, exec, s[4:5]
	s_mov_b64 s[0:1], -1
	v_pk_mul_f32 v[62:63], v[56:57], v[70:71] op_sel_hi:[1,0]
	v_pk_mul_f32 v[56:57], v[54:55], v[70:71] op_sel_hi:[1,0]
	v_cvt_pk_bf16_f32 v54, v58, v59
	v_pk_mul_f32 v[60:61], v[60:61], v[70:71] op_sel_hi:[1,0]
	s_nop 0
	v_cvt_pk_bf16_f32 v55, v60, v61
	v_cvt_pk_bf16_f32 v56, v56, v57
	v_cvt_pk_bf16_f32 v57, v62, v63
	flat_store_dwordx4 v[2:3], v[54:57] offset:256 sc0 sc1
	s_cbranch_vccnz .LBB0_516
	ds_read_b32 v54, v17 offset:2312
	s_mov_b64 s[0:1], 0

; __device__ __forceinline__ unsigned cvt_pk_bf16(float lo, float hi) { unsigned r; asm volatile("v_cvt_pk_bf16_f32 %0, %1, %2" : "=v"(r) : "v"(lo), "v"(hi)); return r; }
;     __device__ __forceinline__ void operator()(const f32x4 (&acc)[2][2][4][2], const Unit& u, int wr, int wc, int fr, int fq) const {
;     ...
;             for (int m = 0; m < 4; ++m) { const int row = row0 + ai * HALF + m * 16; bf16_t* rowp = O + (size_t)row * DM + col0;
;                 float sc = 1.0f; if (SEG) { if (ftab) sc = ftab[(ai * HALF + wr * 64 + m * 16 + fr) * 4 + 2];
;                     else { const float s2 = ss[(size_t)row * 4 + 2]; sc = 1.0f / sqrtf(s2 * (1.0f / 384.0f) + LN_EPS); } }
; #pragma unroll
;                 for (int bj = 0; bj < 2; ++bj) { const f32x4 v0 = acc[ai][bj][m][0] * sc, v1 = acc[ai][bj][m][1] * sc;
;                     u32x4 wv; wv.x = cvt_pk_bf16(v0[0], v0[1]); wv.y = cvt_pk_bf16(v0[2], v0[3]); wv.z = cvt_pk_bf16(v1[0], v1[1]); wv.w = cvt_pk_bf16(v1[2], v1[3]);
;                     *(u32x4*)(rowp + bj * HALF) = wv; } }
.LBB0_518:
	v_lshlrev_b64 v[2:3], 11, v[2:3]
	v_lshl_add_u64 v[2:3], s[6:7], 0, v[2:3]
	v_lshl_add_u64 v[2:3], v[2:3], 0, v[0:1]
	s_waitcnt lgkmcnt(0)
	v_pk_mul_f32 v[52:53], v[52:53], v[54:55] op_sel_hi:[1,0]
	v_pk_mul_f32 v[50:51], v[50:51], v[54:55] op_sel_hi:[1,0]
	v_pk_mul_f32 v[56:57], v[48:49], v[54:55] op_sel_hi:[1,0]
	v_pk_mul_f32 v[48:49], v[46:47], v[54:55] op_sel_hi:[1,0]
	v_cvt_pk_bf16_f32 v46, v50, v51
	v_cvt_pk_bf16_f32 v47, v52, v53
	v_pk_mul_f32 v[42:43], v[42:43], v[54:55] op_sel_hi:[1,0]
	v_cvt_pk_bf16_f32 v48, v48, v49
	v_cvt_pk_bf16_f32 v49, v56, v57
	flat_store_dwordx4 v[2:3], v[46:49] sc0 sc1
	s_and_b64 vcc, exec, s[4:5]
	s_mov_b64 s[0:1], -1
	v_pk_mul_f32 v[46:47], v[40:41], v[54:55] op_sel_hi:[1,0]
	v_pk_mul_f32 v[40:41], v[38:39], v[54:55] op_sel_hi:[1,0]
	v_cvt_pk_bf16_f32 v38, v42, v43
	v_pk_mul_f32 v[44:45], v[44:45], v[54:55] op_sel_hi:[1,0]
	s_nop 0
	v_cvt_pk_bf16_f32 v39, v44, v45
	v_cvt_pk_bf16_f32 v40, v40, v41
	v_cvt_pk_bf16_f32 v41, v46, v47
	flat_store_dwordx4 v[2:3], v[38:41] offset:256 sc0 sc1
	s_cbranch_vccnz .LBB0_520
	ds_read_b32 v38, v17 offset:2568
	s_mov_b64 s[0:1], 0

; __device__ __forceinline__ unsigned cvt_pk_bf16(float lo, float hi) { unsigned r; asm volatile("v_cvt_pk_bf16_f32 %0, %1, %2" : "=v"(r) : "v"(lo), "v"(hi)); return r; }
;     __device__ __forceinline__ void operator()(const f32x4 (&acc)[2][2][4][2], const Unit& u, int wr, int wc, int fr, int fq) const {
;     ...
;             for (int m = 0; m < 4; ++m) { const int row = row0 + ai * HALF + m * 16; bf16_t* rowp = O + (size_t)row * DM + col0;
;                 float sc = 1.0f; if (SEG) { if (ftab) sc = ftab[(ai * HALF + wr * 64 + m * 16 + fr) * 4 + 2];
;                     else { const float s2 = ss[(size_t)row * 4 + 2]; sc = 1.0f / sqrtf(s2 * (1.0f / 384.0f) + LN_EPS); } }
; #pragma unroll
;                 for (int bj = 0; bj < 2; ++bj) { const f32x4 v0 = acc[ai][bj][m][0] * sc, v1 = acc[ai][bj][m][1] * sc;
;                     u32x4 wv; wv.x = cvt_pk_bf16(v0[0], v0[1]); wv.y = cvt_pk_bf16(v0[2], v0[3]); wv.z = cvt_pk_bf16(v1[0], v1[1]); wv.w = cvt_pk_bf16(v1[2], v1[3]);
;                     *(u32x4*)(rowp + bj * HALF) = wv; } }
.LBB0_522:
	v_lshlrev_b64 v[2:3], 11, v[2:3]
	v_lshl_add_u64 v[2:3], s[6:7], 0, v[2:3]
	v_lshl_add_u64 v[2:3], v[2:3], 0, v[0:1]
	s_waitcnt lgkmcnt(0)
	v_pk_mul_f32 v[36:37], v[36:37], v[38:39] op_sel_hi:[1,0]
	v_pk_mul_f32 v[34:35], v[34:35], v[38:39] op_sel_hi:[1,0]
	v_pk_mul_f32 v[40:41], v[32:33], v[38:39] op_sel_hi:[1,0]
	v_pk_mul_f32 v[32:33], v[30:31], v[38:39] op_sel_hi:[1,0]
	v_cvt_pk_bf16_f32 v30, v34, v35
	v_cvt_pk_bf16_f32 v31, v36, v37
	v_pk_mul_f32 v[26:27], v[26:27], v[38:39] op_sel_hi:[1,0]
	v_cvt_pk_bf16_f32 v32, v32, v33
	v_cvt_pk_bf16_f32 v33, v40, v41
	flat_store_dwordx4 v[2:3], v[30:33] sc0 sc1
	s_and_b64 vcc, exec, s[4:5]
	s_mov_b64 s[0:1], -1
	v_pk_mul_f32 v[30:31], v[24:25], v[38:39] op_sel_hi:[1,0]
	v_pk_mul_f32 v[24:25], v[22:23], v[38:39] op_sel_hi:[1,0]
	v_cvt_pk_bf16_f32 v22, v26, v27
	v_pk_mul_f32 v[28:29], v[28:29], v[38:39] op_sel_hi:[1,0]
	s_nop 0
	v_cvt_pk_bf16_f32 v23, v28, v29
	v_cvt_pk_bf16_f32 v24, v24, v25
	v_cvt_pk_bf16_f32 v25, v30, v31
	flat_store_dwordx4 v[2:3], v[22:25] offset:256 sc0 sc1
	s_cbranch_vccnz .LBB0_524
	ds_read_b32 v22, v17 offset:2824
	s_mov_b64 s[0:1], 0

; __device__ __forceinline__ unsigned cvt_pk_bf16(float lo, float hi) { unsigned r; asm volatile("v_cvt_pk_bf16_f32 %0, %1, %2" : "=v"(r) : "v"(lo), "v"(hi)); return r; }
;     __device__ __forceinline__ void operator()(const f32x4 (&acc)[2][2][4][2], const Unit& u, int wr, int wc, int fr, int fq) const {
;     ...
;             for (int m = 0; m < 4; ++m) { const int row = row0 + ai * HALF + m * 16; bf16_t* rowp = O + (size_t)row * DM + col0;
;                 float sc = 1.0f; if (SEG) { if (ftab) sc = ftab[(ai * HALF + wr * 64 + m * 16 + fr) * 4 + 2];
;                     else { const float s2 = ss[(size_t)row * 4 + 2]; sc = 1.0f / sqrtf(s2 * (1.0f / 384.0f) + LN_EPS); } }
; #pragma unroll
;                 for (int bj = 0; bj < 2; ++bj) { const f32x4 v0 = acc[ai][bj][m][0] * sc, v1 = acc[ai][bj][m][1] * sc;
;                     u32x4 wv; wv.x = cvt_pk_bf16(v0[0], v0[1]); wv.y = cvt_pk_bf16(v0[2], v0[3]); wv.z = cvt_pk_bf16(v1[0], v1[1]); wv.w = cvt_pk_bf16(v1[2], v1[3]);
;                     *(u32x4*)(rowp + bj * HALF) = wv; } }
.LBB0_526:
	v_lshlrev_b64 v[2:3], 11, v[2:3]
	v_lshl_add_u64 v[2:3], s[6:7], 0, v[2:3]
	v_lshl_add_u64 v[24:25], v[2:3], 0, v[0:1]
	s_waitcnt lgkmcnt(0)
	v_pk_mul_f32 v[2:3], v[20:21], v[22:23] op_sel_hi:[1,0]
	v_pk_mul_f32 v[18:19], v[18:19], v[22:23] op_sel_hi:[1,0]
	v_pk_mul_f32 v[20:21], v[14:15], v[22:23] op_sel_hi:[1,0]
	v_pk_mul_f32 v[14:15], v[12:13], v[22:23] op_sel_hi:[1,0]
	v_cvt_pk_bf16_f32 v12, v18, v19
	v_cvt_pk_bf16_f32 v13, v2, v3
	v_pk_mul_f32 v[2:3], v[8:9], v[22:23] op_sel_hi:[1,0]
	v_pk_mul_f32 v[4:5], v[4:5], v[22:23] op_sel_hi:[1,0]
	v_cvt_pk_bf16_f32 v14, v14, v15
	v_cvt_pk_bf16_f32 v15, v20, v21
	flat_store_dwordx4 v[24:25], v[12:15] sc0 sc1
	v_pk_mul_f32 v[10:11], v[10:11], v[22:23] op_sel_hi:[1,0]
	v_pk_mul_f32 v[6:7], v[6:7], v[22:23] op_sel_hi:[1,0]
	v_cvt_pk_bf16_f32 v2, v2, v3
	v_cvt_pk_bf16_f32 v3, v10, v11
	v_cvt_pk_bf16_f32 v4, v4, v5
	s_nop 0
	v_cvt_pk_bf16_f32 v5, v6, v7
	flat_store_dwordx4 v[24:25], v[2:5] offset:256 sc0 sc1
